# attention softmax: 12 v_sub_f32 pairs packed into v_pk_add_f32 with op_sel broadcast of the row max (instruction selection in the attention loop), on top of v55
# baseline (speedup 1.0000x reference)
.LBB0_220:
	ds_read_b128 v[212:215], v195 offset:17440
	ds_read_b128 v[216:219], v195 offset:22048
	ds_read_b128 v[220:223], v195 offset:26656
	ds_read_b128 v[224:227], v195 offset:31264
	v_sub_f32_e32 v97, v97, v157
	v_sub_f32_e32 v96, v96, v157
	v_exp_f32_e32 v177, v97
	v_sub_f32_e32 v97, v98, v157
	v_exp_f32_e32 v176, v96
	v_exp_f32_e32 v178, v97
	v_sub_f32_e32 v97, v99, v157
	v_sub_f32_e32 v96, v100, v157
	v_exp_f32_e32 v179, v97
	v_exp_f32_e32 v180, v96
	v_sub_f32_e32 v97, v101, v157
	v_sub_f32_e32 v96, v102, v157
	v_exp_f32_e32 v181, v97
	v_exp_f32_e32 v182, v96
	v_sub_f32_e32 v97, v103, v157
	v_add_f32_e32 v208, v176, v177
	v_exp_f32_e32 v183, v97
	v_add_f32_e32 v208, v178, v208
	v_add_f32_e32 v208, v179, v208
	v_add_f32_e32 v208, v180, v208
	v_add_f32_e32 v208, v181, v208
	v_add_f32_e32 v208, v182, v208
	v_add_f32_e32 v208, v183, v208
	v_cvt_pk_bf16_f32 v176, v176, v177
	v_cvt_pk_bf16_f32 v177, v178, v179
	v_cvt_pk_bf16_f32 v178, v180, v181
	v_cvt_pk_bf16_f32 v179, v182, v183
	s_nop 0
	v_pk_add_f32 v[96:97], v[104:105], v[156:157] op_sel:[0,1] op_sel_hi:[1,1] neg_lo:[0,1] neg_hi:[0,1]
	v_mfma_f32_32x32x16_bf16 v[64:79], v[144:147], v[176:179], v[64:79]
	v_exp_f32_e32 v184, v96
	v_exp_f32_e32 v185, v97
	v_pk_add_f32 v[96:97], v[106:107], v[156:157] op_sel:[0,1] op_sel_hi:[1,1] neg_lo:[0,1] neg_hi:[0,1]
	v_mfma_f32_32x32x16_bf16 v[48:63], v[10:13], v[176:179], v[48:63]
	v_exp_f32_e32 v186, v96
	v_exp_f32_e32 v187, v97
	v_pk_add_f32 v[96:97], v[108:109], v[156:157] op_sel:[0,1] op_sel_hi:[1,1] neg_lo:[0,1] neg_hi:[0,1]
	v_mfma_f32_32x32x16_bf16 v[32:47], v[6:9], v[176:179], v[32:47]
	v_exp_f32_e32 v188, v96
	v_exp_f32_e32 v189, v97
	v_pk_add_f32 v[96:97], v[110:111], v[156:157] op_sel:[0,1] op_sel_hi:[1,1] neg_lo:[0,1] neg_hi:[0,1]
	s_waitcnt lgkmcnt(4)
	v_mfma_f32_32x32x16_bf16 v[16:31], v[2:5], v[176:179], v[16:31]
	v_exp_f32_e32 v190, v96
	v_exp_f32_e32 v191, v97
	ds_read_b128 v[6:9], v195 offset:22080
	ds_read_b128 v[10:13], v195 offset:26688
	ds_read_b128 v[2:5], v195 offset:31296
	v_add_f32_e32 v208, v184, v208
	v_add_f32_e32 v208, v185, v208
	v_add_f32_e32 v208, v186, v208
	v_add_f32_e32 v208, v187, v208
	v_add_f32_e32 v208, v188, v208
	v_add_f32_e32 v208, v189, v208
	v_add_f32_e32 v208, v190, v208
	v_add_f32_e32 v208, v191, v208
	v_cvt_pk_bf16_f32 v144, v184, v185
	v_cvt_pk_bf16_f32 v145, v186, v187
	v_cvt_pk_bf16_f32 v146, v188, v189
	v_cvt_pk_bf16_f32 v147, v190, v191
	v_pk_add_f32 v[96:97], v[80:81], v[156:157] op_sel:[0,1] op_sel_hi:[1,1] neg_lo:[0,1] neg_hi:[0,1]
	s_waitcnt lgkmcnt(3)
	v_mfma_f32_32x32x16_bf16 v[64:79], v[212:215], v[144:147], v[64:79]
	v_exp_f32_e32 v102, v96
	v_exp_f32_e32 v104, v97
	v_pk_add_f32 v[96:97], v[82:83], v[156:157] op_sel:[0,1] op_sel_hi:[1,1] neg_lo:[0,1] neg_hi:[0,1]
	v_mfma_f32_32x32x16_bf16 v[48:63], v[216:219], v[144:147], v[48:63]
	v_exp_f32_e32 v106, v96
	v_exp_f32_e32 v101, v97
	ds_read_b128 v[80:83], v195 offset:17472
	v_pk_add_f32 v[96:97], v[84:85], v[156:157] op_sel:[0,1] op_sel_hi:[1,1] neg_lo:[0,1] neg_hi:[0,1]
	v_mfma_f32_32x32x16_bf16 v[32:47], v[220:223], v[144:147], v[32:47]
	v_exp_f32_e32 v103, v96
	v_exp_f32_e32 v105, v97
	v_pk_add_f32 v[96:97], v[86:87], v[156:157] op_sel:[0,1] op_sel_hi:[1,1] neg_lo:[0,1] neg_hi:[0,1]
	v_mfma_f32_32x32x16_bf16 v[16:31], v[224:227], v[144:147], v[16:31]
	v_exp_f32_e32 v107, v96
	v_exp_f32_e32 v108, v97
	v_add_f32_e32 v208, v102, v208
	v_add_f32_e32 v208, v104, v208
	v_add_f32_e32 v208, v106, v208
	v_add_f32_e32 v208, v101, v208
	v_add_f32_e32 v208, v103, v208
	v_add_f32_e32 v208, v105, v208
	v_add_f32_e32 v208, v107, v208
	v_add_f32_e32 v208, v108, v208
	v_cvt_pk_bf16_f32 v144, v102, v104
	v_cvt_pk_bf16_f32 v145, v106, v101
	v_cvt_pk_bf16_f32 v146, v103, v105
	v_cvt_pk_bf16_f32 v147, v107, v108
	v_pk_add_f32 v[96:97], v[88:89], v[156:157] op_sel:[0,1] op_sel_hi:[1,1] neg_lo:[0,1] neg_hi:[0,1]
	s_waitcnt lgkmcnt(0)
	v_mfma_f32_32x32x16_bf16 v[64:79], v[80:83], v[144:147], v[64:79]
	v_exp_f32_e32 v109, v96
	v_exp_f32_e32 v110, v97
	v_pk_add_f32 v[96:97], v[90:91], v[156:157] op_sel:[0,1] op_sel_hi:[1,1] neg_lo:[0,1] neg_hi:[0,1]
	v_mfma_f32_32x32x16_bf16 v[48:63], v[6:9], v[144:147], v[48:63]
	v_exp_f32_e32 v111, v96
	v_exp_f32_e32 v171, v97
	v_pk_add_f32 v[96:97], v[92:93], v[156:157] op_sel:[0,1] op_sel_hi:[1,1] neg_lo:[0,1] neg_hi:[0,1]
	v_mfma_f32_32x32x16_bf16 v[32:47], v[10:13], v[144:147], v[32:47]
	v_exp_f32_e32 v172, v96
	v_exp_f32_e32 v173, v97
	v_pk_add_f32 v[96:97], v[94:95], v[156:157] op_sel:[0,1] op_sel_hi:[1,1] neg_lo:[0,1] neg_hi:[0,1]
	v_mfma_f32_32x32x16_bf16 v[16:31], v[2:5], v[144:147], v[16:31]
	v_exp_f32_e32 v174, v96
	v_exp_f32_e32 v175, v97
	ds_read_b128 v[84:87], v195 offset:17504
	ds_read_b128 v[88:91], v195 offset:22112
	ds_read_b128 v[92:95], v195 offset:26720
	ds_read_b128 v[96:99], v195 offset:31328
	v_add_f32_e32 v208, v109, v208
	v_add_f32_e32 v208, v110, v208
	v_add_f32_e32 v208, v111, v208
	v_add_f32_e32 v208, v171, v208
	v_add_f32_e32 v208, v172, v208
	v_add_f32_e32 v208, v173, v208
	v_add_f32_e32 v208, v174, v208
	v_add_f32_e32 v208, v175, v208
	v_cvt_pk_bf16_f32 v2, v109, v110
	v_cvt_pk_bf16_f32 v3, v111, v171
	v_cvt_pk_bf16_f32 v4, v172, v173
	v_cvt_pk_bf16_f32 v5, v174, v175
	s_mov_b64 s[6:7], 0x80
	v_lshl_add_u64 v[158:159], v[158:159], 0, s[4:5]
	v_lshl_add_u64 v[160:161], v[160:161], 0, s[6:7]
	s_waitcnt lgkmcnt(0)
	s_barrier
	v_mfma_f32_32x32x16_bf16 v[64:79], v[84:87], v[2:5], v[64:79]
	v_mfma_f32_32x32x16_bf16 v[48:63], v[88:91], v[2:5], v[48:63]
	v_mfma_f32_32x32x16_bf16 v[32:47], v[92:95], v[2:5], v[32:47]
	v_mfma_f32_32x32x16_bf16 v[16:31], v[96:99], v[2:5], v[16:31]
	v_mov_b32_e32 v14, v208
	s_add_i32 s0, s0, 1
	s_cmpk_eq_i32 s0, 0x44
	v_fmac_f32_e32 v14, v168, v0
	s_cbranch_scc1 .LBB0_222
	v_mov_b32_e32 v168, v14
	s_branch .LBB0_216
